# GEMM1 K-loop: last two LDS-DMA pieces of each SP2 load section issued inside the following MFMA section (vmcnt 8->6), on top of ragged-round overlap
# baseline (speedup 1.0000x reference)
; #define PG8_STAGE(bufoff, gbase, voff) do { _Pragma("unroll") for (int _i = 0; _i < 2; ++_i) \
;         __builtin_amdgcn_global_load_lds((const unsigned*)((const char*)(gbase) + (voff)[_i]), (LAS unsigned*)(lds + (bufoff) + ldsw + _i * 8192), 16, 0, 0); } while (0)
; #define PG8_WAIT_V(n) asm volatile("s_waitcnt vmcnt(" #n ")" ::: "memory")
; #define PG8_WAIT_L(n) asm volatile("s_waitcnt lgkmcnt(" #n ")" ::: "memory")
; #define PG8_BAR __builtin_amdgcn_s_barrier()
; #define PG8_SCHED __builtin_amdgcn_sched_barrier(0)
; template <class Epi, class Sched, bool FP8 = false>
; __device__ __forceinline__ void gemm_phase(LAS unsigned char* lds, const Gemm g, const Sched& S, const Epi& E) {
;     ...
;             PG8_LDB(B0, 0, 0); PG8_LDB(B1, 0, 1); PG8_SCHED; PG8_LDA(At, 0, 0); PG8_STAGE(PG8_SA(1, 1), a1 + hstepA, voffA);
;             PG8_WAIT_V(8); PG8_WAIT_L(0); PG8_BAR; PG8_MMA(0, 0, At, B0); PG8_MMA(0, 1, At, B1); PG8_BAR; PG8_SCHED;
;             PG8_LDA(At, 0, 1); PG8_STAGE(PG8_SB(0, 0), b2, voffB); PG8_STAGE(PG8_SB(0, 1), b2 + hstepB, voffB); PG8_STAGE(PG8_SA(0, 0), a2, voffA);
;             PG8_WAIT_V(8); PG8_WAIT_L(0); PG8_BAR; PG8_MMA(1, 0, At, B0); PG8_MMA(1, 1, At, B1); PG8_BAR; PG8_SCHED;
.LBB0_74:
	ds_read_b128 v[16:19], v165
	ds_read_b128 v[20:23], v165 offset:1024
	ds_read_b128 v[24:27], v165 offset:2048
	ds_read_b128 v[28:31], v165 offset:3072
	ds_read_b128 v[0:3], v193
	ds_read_b128 v[4:7], v193 offset:1024
	ds_read_b128 v[8:11], v193 offset:2048
	ds_read_b128 v[12:15], v193 offset:3072
	s_add_u32 s10, s6, 0xfffc0080
	s_addc_u32 s11, s7, -1
	s_cmp_eq_u32 s44, 12
	s_cselect_b32 s43, s1, s11
	s_cselect_b32 s42, s9, s10
	s_cselect_b32 s11, s16, s37
	s_cselect_b32 s10, s33, s35
	v_lshl_add_u64 v[224:225], s[6:7], 0, v[176:177]
	s_add_i32 m0, s48, 0xc000
	ds_read_b128 v[184:187], v194
	ds_read_b128 v[188:191], v194 offset:1024
	ds_read_b128 v[200:203], v194 offset:2048
	ds_read_b128 v[204:207], v194 offset:3072
	ds_read_b128 v[208:211], v194 offset:4096
	ds_read_b128 v[212:215], v194 offset:5120
	ds_read_b128 v[216:219], v194 offset:6144
	ds_read_b128 v[220:223], v194 offset:7168
	global_load_lds_dwordx4 v[224:225], off
	v_lshl_add_u64 v[224:225], s[6:7], 0, v[178:179]
	s_add_i32 m0, s48, 0xe000
	s_nop 0
	global_load_lds_dwordx4 v[224:225], off
	s_waitcnt vmcnt(8)
	s_waitcnt lgkmcnt(0)
	s_barrier
	s_setprio 1
	s_waitcnt lgkmcnt(0)
	v_mfma_scale_f32_16x16x128_f8f6f4 v[156:159], v[16:23], v[184:191], v[156:159], v195, v195 op_sel_hi:[0,0,0]
	v_mfma_scale_f32_16x16x128_f8f6f4 v[148:151], v[24:31], v[184:191], v[148:151], v195, v195 op_sel_hi:[0,0,0]
	v_mfma_scale_f32_16x16x128_f8f6f4 v[140:143], v[16:23], v[200:207], v[140:143], v195, v195 op_sel_hi:[0,0,0]
	v_mfma_scale_f32_16x16x128_f8f6f4 v[136:139], v[24:31], v[200:207], v[136:139], v195, v195 op_sel_hi:[0,0,0]
	v_mfma_scale_f32_16x16x128_f8f6f4 v[124:127], v[16:23], v[208:215], v[124:127], v195, v195 op_sel_hi:[0,0,0]
	v_mfma_scale_f32_16x16x128_f8f6f4 v[120:123], v[24:31], v[208:215], v[120:123], v195, v195 op_sel_hi:[0,0,0]
	v_mfma_scale_f32_16x16x128_f8f6f4 v[108:111], v[16:23], v[216:223], v[108:111], v195, v195 op_sel_hi:[0,0,0]
	v_mfma_scale_f32_16x16x128_f8f6f4 v[104:107], v[24:31], v[216:223], v[104:107], v195, v195 op_sel_hi:[0,0,0]
	s_setprio 0
	s_setprio 1
	v_mfma_scale_f32_16x16x128_f8f6f4 v[152:155], v[0:7], v[184:191], v[152:155], v195, v195 op_sel_hi:[0,0,0]
	v_mfma_scale_f32_16x16x128_f8f6f4 v[144:147], v[8:15], v[184:191], v[144:147], v195, v195 op_sel_hi:[0,0,0]
	v_mfma_scale_f32_16x16x128_f8f6f4 v[132:135], v[0:7], v[200:207], v[132:135], v195, v195 op_sel_hi:[0,0,0]
	v_mfma_scale_f32_16x16x128_f8f6f4 v[128:131], v[8:15], v[200:207], v[128:131], v195, v195 op_sel_hi:[0,0,0]
	v_mfma_scale_f32_16x16x128_f8f6f4 v[116:119], v[0:7], v[208:215], v[116:119], v195, v195 op_sel_hi:[0,0,0]
	v_mfma_scale_f32_16x16x128_f8f6f4 v[112:115], v[8:15], v[208:215], v[112:115], v195, v195 op_sel_hi:[0,0,0]
	v_mfma_scale_f32_16x16x128_f8f6f4 v[100:103], v[0:7], v[216:223], v[100:103], v195, v195 op_sel_hi:[0,0,0]
	v_mfma_scale_f32_16x16x128_f8f6f4 v[96:99], v[8:15], v[216:223], v[96:99], v195, v195 op_sel_hi:[0,0,0]
	s_setprio 0
	s_barrier
	s_add_i32 s45, s62, s47
	v_lshl_add_u64 v[184:185], s[10:11], 0, v[168:169]
	s_mov_b32 m0, s45
	ds_read_b128 v[200:203], v194 offset:16384
	ds_read_b128 v[204:207], v194 offset:17408
	ds_read_b128 v[208:211], v194 offset:18432
	ds_read_b128 v[212:215], v194 offset:19456
	ds_read_b128 v[216:219], v194 offset:20480
	ds_read_b128 v[220:223], v194 offset:21504
	ds_read_b128 v[224:227], v194 offset:22528
	ds_read_b128 v[228:231], v194 offset:23552
	global_load_lds_dwordx4 v[184:185], off
	s_add_i32 m0, s45, 0x2000
	s_add_u32 s68, s10, 0x80000
	v_lshl_add_u64 v[186:187], s[10:11], 0, v[172:173]
	s_addc_u32 s69, s11, 0
	s_add_i32 s45, s63, s47
	global_load_lds_dwordx4 v[186:187], off
	v_lshl_add_u64 v[188:189], s[68:69], 0, v[168:169]
	s_mov_b32 m0, s45
	v_lshl_add_u64 v[190:191], s[42:43], 0, v[170:171]
	global_load_lds_dwordx4 v[188:189], off
	v_lshl_add_u64 v[188:189], s[68:69], 0, v[172:173]
	s_add_i32 m0, s45, 0x2000
	s_nop 0
	global_load_lds_dwordx4 v[188:189], off
	v_lshl_add_u64 v[188:189], s[42:43], 0, v[166:167]
	s_waitcnt vmcnt(6)
	s_waitcnt lgkmcnt(0)
	s_barrier
	s_setprio 1
	s_waitcnt lgkmcnt(0)
	v_mfma_scale_f32_16x16x128_f8f6f4 v[92:95], v[16:23], v[200:207], v[92:95], v195, v195 op_sel_hi:[0,0,0]
	v_mfma_scale_f32_16x16x128_f8f6f4 v[88:91], v[24:31], v[200:207], v[88:91], v195, v195 op_sel_hi:[0,0,0]
	s_mov_b32 m0, s48
	v_mfma_scale_f32_16x16x128_f8f6f4 v[76:79], v[16:23], v[208:215], v[76:79], v195, v195 op_sel_hi:[0,0,0]
	global_load_lds_dwordx4 v[188:189], off
	v_mfma_scale_f32_16x16x128_f8f6f4 v[72:75], v[24:31], v[208:215], v[72:75], v195, v195 op_sel_hi:[0,0,0]
	v_mfma_scale_f32_16x16x128_f8f6f4 v[60:63], v[16:23], v[216:223], v[60:63], v195, v195 op_sel_hi:[0,0,0]
	v_mfma_scale_f32_16x16x128_f8f6f4 v[56:59], v[24:31], v[216:223], v[56:59], v195, v195 op_sel_hi:[0,0,0]
	v_mfma_scale_f32_16x16x128_f8f6f4 v[44:47], v[16:23], v[224:231], v[44:47], v195, v195 op_sel_hi:[0,0,0]
	v_mfma_scale_f32_16x16x128_f8f6f4 v[40:43], v[24:31], v[224:231], v[40:43], v195, v195 op_sel_hi:[0,0,0]
	s_setprio 0
	s_setprio 1
	v_mfma_scale_f32_16x16x128_f8f6f4 v[84:87], v[0:7], v[200:207], v[84:87], v195, v195 op_sel_hi:[0,0,0]
	v_mfma_scale_f32_16x16x128_f8f6f4 v[80:83], v[8:15], v[200:207], v[80:83], v195, v195 op_sel_hi:[0,0,0]
	s_mov_b32 m0, s49
	v_mfma_scale_f32_16x16x128_f8f6f4 v[68:71], v[0:7], v[208:215], v[68:71], v195, v195 op_sel_hi:[0,0,0]
	global_load_lds_dwordx4 v[190:191], off
	v_mfma_scale_f32_16x16x128_f8f6f4 v[64:67], v[8:15], v[208:215], v[64:67], v195, v195 op_sel_hi:[0,0,0]
	v_mfma_scale_f32_16x16x128_f8f6f4 v[52:55], v[0:7], v[216:223], v[52:55], v195, v195 op_sel_hi:[0,0,0]
	v_mfma_scale_f32_16x16x128_f8f6f4 v[48:51], v[8:15], v[216:223], v[48:51], v195, v195 op_sel_hi:[0,0,0]
	v_mfma_scale_f32_16x16x128_f8f6f4 v[36:39], v[0:7], v[224:231], v[36:39], v195, v195 op_sel_hi:[0,0,0]
	v_mfma_scale_f32_16x16x128_f8f6f4 v[32:35], v[8:15], v[224:231], v[32:35], v195, v195 op_sel_hi:[0,0,0]
	s_setprio 0
	s_barrier
; #define PG8_STAGE(bufoff, gbase, voff) do { _Pragma("unroll") for (int _i = 0; _i < 2; ++_i) \
;         __builtin_amdgcn_global_load_lds((const unsigned*)((const char*)(gbase) + (voff)[_i]), (LAS unsigned*)(lds + (bufoff) + ldsw + _i * 8192), 16, 0, 0); } while (0)
; #define PG8_WAIT_V(n) asm volatile("s_waitcnt vmcnt(" #n ")" ::: "memory")
; #define PG8_WAIT_L(n) asm volatile("s_waitcnt lgkmcnt(" #n ")" ::: "memory")
; #define PG8_BAR __builtin_amdgcn_s_barrier()
; #define PG8_SCHED __builtin_amdgcn_sched_barrier(0)
; template <class Epi, class Sched, bool FP8 = false>
; __device__ __forceinline__ void gemm_phase(LAS unsigned char* lds, const Gemm g, const Sched& S, const Epi& E) {
;     ...
;             PG8_LDB(B0, 1, 0); PG8_LDB(B1, 1, 1); PG8_SCHED; PG8_LDA(At, 1, 0); PG8_STAGE(PG8_SA(0, 1), a2 + hstepA, voffA);
;             PG8_WAIT_V(8); PG8_WAIT_L(0); PG8_BAR; PG8_MMA(0, 0, At, B0); PG8_MMA(0, 1, At, B1); PG8_BAR; PG8_SCHED;
;             PG8_LDA(At, 1, 1); PG8_STAGE(PG8_SB(1, 0), b3, voffB); PG8_STAGE(PG8_SB(1, 1), b3 + hstepB, voffB); PG8_STAGE(PG8_SA(1, 0), a3, voffA);
;             PG8_WAIT_V(8); PG8_WAIT_L(0); PG8_BAR; PG8_MMA(1, 0, At, B0); PG8_MMA(1, 1, At, B1); PG8_BAR; PG8_SCHED;
;         }
	s_add_i32 s45, 0, 0x18000
	s_add_i32 s68, 0, 0x1c000
	v_add_u32_e32 v12, s45, v163
	v_add_u32_e32 v28, s68, v163
	ds_read_b128 v[0:3], v12
	ds_read_b128 v[4:7], v12 offset:1024
	ds_read_b128 v[8:11], v12 offset:2048
	ds_read_b128 v[12:15], v12 offset:3072
	ds_read_b128 v[16:19], v28
	ds_read_b128 v[20:23], v28 offset:1024
	ds_read_b128 v[24:27], v28 offset:2048
	ds_read_b128 v[28:31], v28 offset:3072
	s_add_u32 s42, s42, 0x40000
	s_addc_u32 s43, s43, 0
	s_mov_b32 m0, s50
	v_lshl_add_u64 v[232:233], s[42:43], 0, v[166:167]
	ds_read_b128 v[200:203], v194 offset:32768
	ds_read_b128 v[204:207], v194 offset:33792
	ds_read_b128 v[208:211], v194 offset:34816
	ds_read_b128 v[212:215], v194 offset:35840
	ds_read_b128 v[216:219], v194 offset:36864
	ds_read_b128 v[220:223], v194 offset:37888
	ds_read_b128 v[224:227], v194 offset:38912
	ds_read_b128 v[228:231], v194 offset:39936
	global_load_lds_dwordx4 v[232:233], off
	v_lshl_add_u64 v[232:233], s[42:43], 0, v[170:171]
	s_mov_b32 m0, s51
	s_nop 0
	global_load_lds_dwordx4 v[232:233], off
	s_waitcnt vmcnt(8)
	s_waitcnt lgkmcnt(0)
	s_barrier
	s_setprio 1
	s_waitcnt lgkmcnt(0)
	v_mfma_scale_f32_16x16x128_f8f6f4 v[156:159], v[0:7], v[200:207], v[156:159], v195, v195 op_sel_hi:[0,0,0]
	v_mfma_scale_f32_16x16x128_f8f6f4 v[148:151], v[8:15], v[200:207], v[148:151], v195, v195 op_sel_hi:[0,0,0]
	v_mfma_scale_f32_16x16x128_f8f6f4 v[140:143], v[0:7], v[208:215], v[140:143], v195, v195 op_sel_hi:[0,0,0]
	v_mfma_scale_f32_16x16x128_f8f6f4 v[136:139], v[8:15], v[208:215], v[136:139], v195, v195 op_sel_hi:[0,0,0]
	v_mfma_scale_f32_16x16x128_f8f6f4 v[124:127], v[0:7], v[216:223], v[124:127], v195, v195 op_sel_hi:[0,0,0]
	v_mfma_scale_f32_16x16x128_f8f6f4 v[120:123], v[8:15], v[216:223], v[120:123], v195, v195 op_sel_hi:[0,0,0]
	v_mfma_scale_f32_16x16x128_f8f6f4 v[108:111], v[0:7], v[224:231], v[108:111], v195, v195 op_sel_hi:[0,0,0]
	v_mfma_scale_f32_16x16x128_f8f6f4 v[104:107], v[8:15], v[224:231], v[104:107], v195, v195 op_sel_hi:[0,0,0]
	s_setprio 0
	s_setprio 1
	v_mfma_scale_f32_16x16x128_f8f6f4 v[152:155], v[16:23], v[200:207], v[152:155], v195, v195 op_sel_hi:[0,0,0]
	v_mfma_scale_f32_16x16x128_f8f6f4 v[144:147], v[24:31], v[200:207], v[144:147], v195, v195 op_sel_hi:[0,0,0]
	v_mfma_scale_f32_16x16x128_f8f6f4 v[132:135], v[16:23], v[208:215], v[132:135], v195, v195 op_sel_hi:[0,0,0]
	v_mfma_scale_f32_16x16x128_f8f6f4 v[128:131], v[24:31], v[208:215], v[128:131], v195, v195 op_sel_hi:[0,0,0]
	v_mfma_scale_f32_16x16x128_f8f6f4 v[116:119], v[16:23], v[216:223], v[116:119], v195, v195 op_sel_hi:[0,0,0]
	v_mfma_scale_f32_16x16x128_f8f6f4 v[112:115], v[24:31], v[216:223], v[112:115], v195, v195 op_sel_hi:[0,0,0]
	v_mfma_scale_f32_16x16x128_f8f6f4 v[100:103], v[16:23], v[224:231], v[100:103], v195, v195 op_sel_hi:[0,0,0]
	v_mfma_scale_f32_16x16x128_f8f6f4 v[96:99], v[24:31], v[224:231], v[96:99], v195, v195 op_sel_hi:[0,0,0]
	s_setprio 0
	s_barrier
	s_add_i32 s42, s45, s47
	v_lshl_add_u64 v[184:185], v[184:185], 0, s[22:23]
	s_mov_b32 m0, s42
	ds_read_b128 v[200:203], v194 offset:49152
	ds_read_b128 v[204:207], v194 offset:50176
	ds_read_b128 v[208:211], v194 offset:51200
	ds_read_b128 v[212:215], v194 offset:52224
	ds_read_b128 v[216:219], v194 offset:53248
	ds_read_b128 v[220:223], v194 offset:54272
	ds_read_b128 v[224:227], v194 offset:55296
	ds_read_b128 v[228:231], v194 offset:56320
	global_load_lds_dwordx4 v[184:185], off
	s_add_i32 m0, s42, 0x2000
	s_add_u32 s10, s10, 0x80080
	v_lshl_add_u64 v[184:185], v[186:187], 0, s[22:23]
	s_addc_u32 s11, s11, 0
	s_add_i32 s42, s68, s47
	global_load_lds_dwordx4 v[184:185], off
	v_lshl_add_u64 v[184:185], s[10:11], 0, v[168:169]
	s_mov_b32 m0, s42
	s_nop 0
	global_load_lds_dwordx4 v[184:185], off
	v_lshl_add_u64 v[184:185], s[10:11], 0, v[172:173]
	s_add_i32 m0, s42, 0x2000
	s_nop 0
	global_load_lds_dwordx4 v[184:185], off
	v_lshl_add_u64 v[186:187], v[188:189], 0, s[22:23]
	v_lshl_add_u64 v[188:189], v[190:191], 0, s[22:23]
	s_waitcnt vmcnt(6)
	s_waitcnt lgkmcnt(0)
	s_barrier
	s_setprio 1
	s_waitcnt lgkmcnt(0)
	v_mfma_scale_f32_16x16x128_f8f6f4 v[92:95], v[0:7], v[200:207], v[92:95], v195, v195 op_sel_hi:[0,0,0]
	v_mfma_scale_f32_16x16x128_f8f6f4 v[88:91], v[8:15], v[200:207], v[88:91], v195, v195 op_sel_hi:[0,0,0]
	s_mov_b32 m0, s53
	v_mfma_scale_f32_16x16x128_f8f6f4 v[76:79], v[0:7], v[208:215], v[76:79], v195, v195 op_sel_hi:[0,0,0]
	global_load_lds_dwordx4 v[186:187], off
	v_mfma_scale_f32_16x16x128_f8f6f4 v[72:75], v[8:15], v[208:215], v[72:75], v195, v195 op_sel_hi:[0,0,0]
	v_mfma_scale_f32_16x16x128_f8f6f4 v[60:63], v[0:7], v[216:223], v[60:63], v195, v195 op_sel_hi:[0,0,0]
	v_mfma_scale_f32_16x16x128_f8f6f4 v[56:59], v[8:15], v[216:223], v[56:59], v195, v195 op_sel_hi:[0,0,0]
	v_mfma_scale_f32_16x16x128_f8f6f4 v[44:47], v[0:7], v[224:231], v[44:47], v195, v195 op_sel_hi:[0,0,0]
	v_mfma_scale_f32_16x16x128_f8f6f4 v[40:43], v[8:15], v[224:231], v[40:43], v195, v195 op_sel_hi:[0,0,0]
	s_setprio 0
	s_setprio 1
	v_mfma_scale_f32_16x16x128_f8f6f4 v[84:87], v[16:23], v[200:207], v[84:87], v195, v195 op_sel_hi:[0,0,0]
	v_mfma_scale_f32_16x16x128_f8f6f4 v[80:83], v[24:31], v[200:207], v[80:83], v195, v195 op_sel_hi:[0,0,0]
	s_mov_b32 m0, s54
	v_mfma_scale_f32_16x16x128_f8f6f4 v[68:71], v[16:23], v[208:215], v[68:71], v195, v195 op_sel_hi:[0,0,0]
	global_load_lds_dwordx4 v[188:189], off
	v_mfma_scale_f32_16x16x128_f8f6f4 v[64:67], v[24:31], v[208:215], v[64:67], v195, v195 op_sel_hi:[0,0,0]
	v_mfma_scale_f32_16x16x128_f8f6f4 v[52:55], v[16:23], v[216:223], v[52:55], v195, v195 op_sel_hi:[0,0,0]
	v_mfma_scale_f32_16x16x128_f8f6f4 v[48:51], v[24:31], v[216:223], v[48:51], v195, v195 op_sel_hi:[0,0,0]
	v_mfma_scale_f32_16x16x128_f8f6f4 v[36:39], v[16:23], v[224:231], v[36:39], v195, v195 op_sel_hi:[0,0,0]
	v_mfma_scale_f32_16x16x128_f8f6f4 v[32:35], v[24:31], v[224:231], v[32:35], v195, v195 op_sel_hi:[0,0,0]
	s_setprio 0
	s_barrier
	s_add_i32 s44, s44, 2
	s_add_u32 s6, s6, 0x100
	s_addc_u32 s7, s7, 0
	s_add_u32 s35, s35, 0x100
	s_addc_u32 s37, s37, 0
	s_cmp_gt_u32 s44, 13
	s_cbranch_scc0 .LBB0_74
	s_and_b64 vcc, exec, s[24:25]
	s_cbranch_vccz .LBB0_77
	s_barrier
